# SwiGLU epilogues (P1, P10): tile-store addresses strength-reduced (first = row*pitch+base+col as before, each later one = previous + scalar row step in one 64-bit add; seven v_mad_i64_i32 and row-offs
# speedup vs baseline: 1.0031x; 1.0004x over previous
; __device__ __forceinline__ unsigned cvt_pk_bf16(float lo, float hi) { unsigned r; asm volatile("v_cvt_pk_bf16_f32 %0, %1, %2" : "=v"(r) : "v"(lo), "v"(hi)); return r; }
; __device__ __forceinline__ f32x2p silu_mul2(f32x2p g, f32x2p u) {
;     const f32x2p t = g * (-1.4426950408889634f); f32x2p e; e.x = __builtin_amdgcn_exp2f(t.x); e.y = __builtin_amdgcn_exp2f(t.y);
;     const f32x2p d = e + 1.0f; f32x2p r; r.x = __builtin_amdgcn_rcpf(d.x); r.y = __builtin_amdgcn_rcpf(d.y);
;     return (g * u) * r;
; }
;     __device__ __forceinline__ void operator()(const f32x4 (&acc)[2][2][4][2], const Unit& u, int wr, int wc, int fr, int fq) const {
;         const int row0 = u.pm * BM + wr * 64 + fr, col0 = u.pn * HALF + wc * 32 + 8 * fq;
; #pragma unroll
;         for (int ai = 0; ai < 2; ++ai)
; #pragma unroll
;             for (int m = 0; m < 4; ++m) { bf16_t* rowp = O + (size_t)(row0 + ai * HALF + m * 16) * ldc + col0;
;                 const f32x4 g0 = acc[ai][0][m][0], g1 = acc[ai][0][m][1], u0 = acc[ai][1][m][0], u1 = acc[ai][1][m][1];
;                 const f32x2p a = silu_mul2((f32x2p){g0[0], g0[1]}, (f32x2p){u0[0], u0[1]}), b = silu_mul2((f32x2p){g0[2], g0[3]}, (f32x2p){u0[2], u0[3]});
;                 const f32x2p c = silu_mul2((f32x2p){g1[0], g1[1]}, (f32x2p){u1[0], u1[1]}), d = silu_mul2((f32x2p){g1[2], g1[3]}, (f32x2p){u1[2], u1[3]});
;                 u32x4 w; w.x = cvt_pk_bf16(a.x, a.y); w.y = cvt_pk_bf16(b.x, b.y); w.z = cvt_pk_bf16(c.x, c.y); w.w = cvt_pk_bf16(d.x, d.y);
;                 *(u32x4*)rowp = w; }
.LBB0_272:
	v_pk_mul_f32 v[158:159], v[124:125], s[8:9] op_sel_hi:[1,0]
	v_pk_mul_f32 v[160:161], v[126:127], s[8:9] op_sel_hi:[1,0]
	v_pk_mul_f32 v[122:123], v[126:127], v[122:123]
	v_pk_mul_f32 v[120:121], v[124:125], v[120:121]
	v_pk_mul_f32 v[124:125], v[116:117], s[8:9] op_sel_hi:[1,0]
	v_pk_mul_f32 v[126:127], v[118:119], s[8:9] op_sel_hi:[1,0]
	v_exp_f32_e32 v158, v158
	v_exp_f32_e32 v159, v159
	v_exp_f32_e32 v160, v160
	v_exp_f32_e32 v161, v161
	v_exp_f32_e32 v124, v124
	v_exp_f32_e32 v125, v125
	v_exp_f32_e32 v126, v126
	v_exp_f32_e32 v127, v127
	v_pk_add_f32 v[158:159], v[158:159], 1.0 op_sel_hi:[1,0]
	v_pk_add_f32 v[160:161], v[160:161], 1.0 op_sel_hi:[1,0]
	v_pk_add_f32 v[124:125], v[124:125], 1.0 op_sel_hi:[1,0]
	v_pk_add_f32 v[126:127], v[126:127], 1.0 op_sel_hi:[1,0]
	v_readlane_b32 s22, v254, 15
	v_rcp_f32_e32 v158, v158
	v_rcp_f32_e32 v159, v159
	v_rcp_f32_e32 v160, v160
	v_rcp_f32_e32 v161, v161
	v_rcp_f32_e32 v124, v124
	v_rcp_f32_e32 v125, v125
	v_rcp_f32_e32 v126, v126
	v_rcp_f32_e32 v127, v127
	v_lshl_add_u32 v146, s43, 7, v150
	v_readlane_b32 s23, v254, 16
	v_lshl_add_u32 v154, s20, 8, v148
	v_ashrrev_i32_e32 v147, 31, v146
	v_mov_b64_e32 v[144:145], s[22:23]
	s_lshl_b32 s100, s42, 4
	s_mov_b32 s101, 0
	s_mul_i32 s96, s42, 0x50
	s_mov_b32 s97, 0
	v_mad_i64_i32 v[156:157], s[22:23], v154, s42, v[144:145]
	v_lshlrev_b64 v[146:147], 1, v[146:147]
	v_pk_mul_f32 v[114:115], v[118:119], v[114:115]
	v_pk_mul_f32 v[112:113], v[116:117], v[112:113]
	v_lshl_add_u64 v[228:229], v[156:157], 0, v[146:147]
	v_pk_mul_f32 v[120:121], v[158:159], v[120:121]
	v_pk_mul_f32 v[122:123], v[160:161], v[122:123]
	v_pk_mul_f32 v[116:117], v[124:125], v[112:113]
	v_pk_mul_f32 v[118:119], v[126:127], v[114:115]
	v_cvt_pk_bf16_f32 v112, v120, v121
	v_cvt_pk_bf16_f32 v113, v122, v123
	v_cvt_pk_bf16_f32 v114, v116, v117
	v_pk_mul_f32 v[116:117], v[110:111], s[8:9] op_sel_hi:[1,0]
	v_cvt_pk_bf16_f32 v115, v118, v119
	global_store_dwordx4 v[228:229], v[112:115], off
	v_pk_mul_f32 v[106:107], v[110:111], v[106:107]
	v_pk_mul_f32 v[104:105], v[108:109], v[104:105]
	v_pk_mul_f32 v[114:115], v[108:109], s[8:9] op_sel_hi:[1,0]
	v_pk_mul_f32 v[108:109], v[100:101], s[8:9] op_sel_hi:[1,0]
	v_pk_mul_f32 v[110:111], v[102:103], s[8:9] op_sel_hi:[1,0]
	v_exp_f32_e32 v114, v114
	v_exp_f32_e32 v115, v115
	v_exp_f32_e32 v116, v116
	v_exp_f32_e32 v117, v117
	v_exp_f32_e32 v108, v108
	v_exp_f32_e32 v109, v109
	v_exp_f32_e32 v110, v110
	v_exp_f32_e32 v111, v111
	v_pk_add_f32 v[114:115], v[114:115], 1.0 op_sel_hi:[1,0]
	v_pk_add_f32 v[116:117], v[116:117], 1.0 op_sel_hi:[1,0]
	v_pk_add_f32 v[108:109], v[108:109], 1.0 op_sel_hi:[1,0]
	v_pk_add_f32 v[110:111], v[110:111], 1.0 op_sel_hi:[1,0]
	v_rcp_f32_e32 v114, v114
	v_rcp_f32_e32 v115, v115
	v_rcp_f32_e32 v116, v116
	v_rcp_f32_e32 v117, v117
	v_rcp_f32_e32 v108, v108
	v_rcp_f32_e32 v109, v109
	v_rcp_f32_e32 v110, v110
	v_rcp_f32_e32 v111, v111
	v_pk_mul_f32 v[98:99], v[102:103], v[98:99]
	v_pk_mul_f32 v[96:97], v[100:101], v[96:97]
	v_lshl_add_u64 v[228:229], v[228:229], 0, s[100:101]
	v_pk_mul_f32 v[104:105], v[114:115], v[104:105]
	v_pk_mul_f32 v[106:107], v[116:117], v[106:107]
	v_pk_mul_f32 v[100:101], v[108:109], v[96:97]
	v_pk_mul_f32 v[102:103], v[110:111], v[98:99]
	v_cvt_pk_bf16_f32 v96, v104, v105
	v_cvt_pk_bf16_f32 v97, v106, v107
	v_cvt_pk_bf16_f32 v98, v100, v101
	v_pk_mul_f32 v[100:101], v[94:95], s[8:9] op_sel_hi:[1,0]
	v_cvt_pk_bf16_f32 v99, v102, v103
	global_store_dwordx4 v[228:229], v[96:99], off
	v_pk_mul_f32 v[90:91], v[94:95], v[90:91]
	v_pk_mul_f32 v[88:89], v[92:93], v[88:89]
	v_pk_mul_f32 v[98:99], v[92:93], s[8:9] op_sel_hi:[1,0]
	v_pk_mul_f32 v[92:93], v[84:85], s[8:9] op_sel_hi:[1,0]
	v_pk_mul_f32 v[94:95], v[86:87], s[8:9] op_sel_hi:[1,0]
	v_exp_f32_e32 v98, v98
	v_exp_f32_e32 v99, v99
	v_exp_f32_e32 v100, v100
	v_exp_f32_e32 v101, v101
	v_exp_f32_e32 v92, v92
	v_exp_f32_e32 v93, v93
	v_exp_f32_e32 v94, v94
	v_exp_f32_e32 v95, v95
	v_pk_add_f32 v[98:99], v[98:99], 1.0 op_sel_hi:[1,0]
	v_pk_add_f32 v[100:101], v[100:101], 1.0 op_sel_hi:[1,0]
	v_pk_add_f32 v[92:93], v[92:93], 1.0 op_sel_hi:[1,0]
	v_pk_add_f32 v[94:95], v[94:95], 1.0 op_sel_hi:[1,0]
	v_rcp_f32_e32 v98, v98
	v_rcp_f32_e32 v99, v99
	v_rcp_f32_e32 v100, v100
	v_rcp_f32_e32 v101, v101
	v_rcp_f32_e32 v92, v92
	v_rcp_f32_e32 v93, v93
	v_rcp_f32_e32 v94, v94
	v_rcp_f32_e32 v95, v95
	v_pk_mul_f32 v[82:83], v[86:87], v[82:83]
	v_pk_mul_f32 v[80:81], v[84:85], v[80:81]
	v_lshl_add_u64 v[228:229], v[228:229], 0, s[100:101]
	v_pk_mul_f32 v[88:89], v[98:99], v[88:89]
	v_pk_mul_f32 v[90:91], v[100:101], v[90:91]
	v_pk_mul_f32 v[84:85], v[92:93], v[80:81]
	v_pk_mul_f32 v[86:87], v[94:95], v[82:83]
	v_cvt_pk_bf16_f32 v80, v88, v89
	v_cvt_pk_bf16_f32 v81, v90, v91
	v_cvt_pk_bf16_f32 v82, v84, v85
	v_pk_mul_f32 v[84:85], v[78:79], s[8:9] op_sel_hi:[1,0]
	v_cvt_pk_bf16_f32 v83, v86, v87
	global_store_dwordx4 v[228:229], v[80:83], off
	v_pk_mul_f32 v[74:75], v[78:79], v[74:75]
	v_pk_mul_f32 v[72:73], v[76:77], v[72:73]
	v_pk_mul_f32 v[82:83], v[76:77], s[8:9] op_sel_hi:[1,0]
	v_pk_mul_f32 v[76:77], v[68:69], s[8:9] op_sel_hi:[1,0]
	v_pk_mul_f32 v[78:79], v[70:71], s[8:9] op_sel_hi:[1,0]
	v_exp_f32_e32 v82, v82
	v_exp_f32_e32 v83, v83
	v_exp_f32_e32 v84, v84
	v_exp_f32_e32 v85, v85
	v_exp_f32_e32 v76, v76
	v_exp_f32_e32 v77, v77
	v_exp_f32_e32 v78, v78
	v_exp_f32_e32 v79, v79
	v_pk_add_f32 v[82:83], v[82:83], 1.0 op_sel_hi:[1,0]
	v_pk_add_f32 v[84:85], v[84:85], 1.0 op_sel_hi:[1,0]
	v_pk_add_f32 v[76:77], v[76:77], 1.0 op_sel_hi:[1,0]
	v_pk_add_f32 v[78:79], v[78:79], 1.0 op_sel_hi:[1,0]
	v_rcp_f32_e32 v82, v82
	v_rcp_f32_e32 v83, v83
; __device__ __forceinline__ unsigned cvt_pk_bf16(float lo, float hi) { unsigned r; asm volatile("v_cvt_pk_bf16_f32 %0, %1, %2" : "=v"(r) : "v"(lo), "v"(hi)); return r; }
; __device__ __forceinline__ f32x2p silu_mul2(f32x2p g, f32x2p u) {
;     const f32x2p t = g * (-1.4426950408889634f); f32x2p e; e.x = __builtin_amdgcn_exp2f(t.x); e.y = __builtin_amdgcn_exp2f(t.y);
;     const f32x2p d = e + 1.0f; f32x2p r; r.x = __builtin_amdgcn_rcpf(d.x); r.y = __builtin_amdgcn_rcpf(d.y);
;     return (g * u) * r;
; }
;     __device__ __forceinline__ void operator()(const f32x4 (&acc)[2][2][4][2], const Unit& u, int wr, int wc, int fr, int fq) const {
;     ...
;             for (int m = 0; m < 4; ++m) { bf16_t* rowp = O + (size_t)(row0 + ai * HALF + m * 16) * ldc + col0;
;                 const f32x4 g0 = acc[ai][0][m][0], g1 = acc[ai][0][m][1], u0 = acc[ai][1][m][0], u1 = acc[ai][1][m][1];
;                 const f32x2p a = silu_mul2((f32x2p){g0[0], g0[1]}, (f32x2p){u0[0], u0[1]}), b = silu_mul2((f32x2p){g0[2], g0[3]}, (f32x2p){u0[2], u0[3]});
;                 const f32x2p c = silu_mul2((f32x2p){g1[0], g1[1]}, (f32x2p){u1[0], u1[1]}), d = silu_mul2((f32x2p){g1[2], g1[3]}, (f32x2p){u1[2], u1[3]});
;                 u32x4 w; w.x = cvt_pk_bf16(a.x, a.y); w.y = cvt_pk_bf16(b.x, b.y); w.z = cvt_pk_bf16(c.x, c.y); w.w = cvt_pk_bf16(d.x, d.y);
;                 *(u32x4*)rowp = w; }
	v_rcp_f32_e32 v84, v84
	v_rcp_f32_e32 v85, v85
	v_rcp_f32_e32 v76, v76
	v_rcp_f32_e32 v77, v77
	v_rcp_f32_e32 v78, v78
	v_rcp_f32_e32 v79, v79
	v_pk_mul_f32 v[66:67], v[70:71], v[66:67]
	v_pk_mul_f32 v[64:65], v[68:69], v[64:65]
	v_lshl_add_u64 v[228:229], v[228:229], 0, s[100:101]
	v_pk_mul_f32 v[72:73], v[82:83], v[72:73]
	v_pk_mul_f32 v[74:75], v[84:85], v[74:75]
	v_pk_mul_f32 v[68:69], v[76:77], v[64:65]
	v_pk_mul_f32 v[70:71], v[78:79], v[66:67]
	v_cvt_pk_bf16_f32 v64, v72, v73
	v_cvt_pk_bf16_f32 v65, v74, v75
	v_cvt_pk_bf16_f32 v66, v68, v69
	v_pk_mul_f32 v[68:69], v[62:63], s[8:9] op_sel_hi:[1,0]
	v_cvt_pk_bf16_f32 v67, v70, v71
	global_store_dwordx4 v[228:229], v[64:67], off
	v_pk_mul_f32 v[58:59], v[62:63], v[58:59]
	v_pk_mul_f32 v[56:57], v[60:61], v[56:57]
	v_pk_mul_f32 v[66:67], v[60:61], s[8:9] op_sel_hi:[1,0]
	v_pk_mul_f32 v[60:61], v[52:53], s[8:9] op_sel_hi:[1,0]
	v_pk_mul_f32 v[62:63], v[54:55], s[8:9] op_sel_hi:[1,0]
	v_exp_f32_e32 v66, v66
	v_exp_f32_e32 v67, v67
	v_exp_f32_e32 v68, v68
	v_exp_f32_e32 v69, v69
	v_exp_f32_e32 v60, v60
	v_exp_f32_e32 v61, v61
	v_exp_f32_e32 v62, v62
	v_exp_f32_e32 v63, v63
	v_pk_add_f32 v[66:67], v[66:67], 1.0 op_sel_hi:[1,0]
	v_pk_add_f32 v[68:69], v[68:69], 1.0 op_sel_hi:[1,0]
	v_pk_add_f32 v[60:61], v[60:61], 1.0 op_sel_hi:[1,0]
	v_pk_add_f32 v[62:63], v[62:63], 1.0 op_sel_hi:[1,0]
	v_rcp_f32_e32 v66, v66
	v_rcp_f32_e32 v67, v67
	v_rcp_f32_e32 v68, v68
	v_rcp_f32_e32 v69, v69
	v_rcp_f32_e32 v60, v60
	v_rcp_f32_e32 v61, v61
	v_rcp_f32_e32 v62, v62
	v_rcp_f32_e32 v63, v63
	v_pk_mul_f32 v[50:51], v[54:55], v[50:51]
	v_pk_mul_f32 v[48:49], v[52:53], v[48:49]
	v_lshl_add_u64 v[228:229], v[228:229], 0, s[96:97]
	v_pk_mul_f32 v[56:57], v[66:67], v[56:57]
	v_pk_mul_f32 v[58:59], v[68:69], v[58:59]
	v_pk_mul_f32 v[52:53], v[60:61], v[48:49]
	v_pk_mul_f32 v[54:55], v[62:63], v[50:51]
	v_cvt_pk_bf16_f32 v48, v56, v57
	v_cvt_pk_bf16_f32 v49, v58, v59
	v_cvt_pk_bf16_f32 v50, v52, v53
	v_pk_mul_f32 v[52:53], v[46:47], s[8:9] op_sel_hi:[1,0]
	v_cvt_pk_bf16_f32 v51, v54, v55
	global_store_dwordx4 v[228:229], v[48:51], off
	v_pk_mul_f32 v[42:43], v[46:47], v[42:43]
	v_pk_mul_f32 v[40:41], v[44:45], v[40:41]
	v_pk_mul_f32 v[50:51], v[44:45], s[8:9] op_sel_hi:[1,0]
	v_pk_mul_f32 v[44:45], v[36:37], s[8:9] op_sel_hi:[1,0]
	v_pk_mul_f32 v[46:47], v[38:39], s[8:9] op_sel_hi:[1,0]
	v_exp_f32_e32 v50, v50
	v_exp_f32_e32 v51, v51
	v_exp_f32_e32 v52, v52
	v_exp_f32_e32 v53, v53
	v_exp_f32_e32 v44, v44
	v_exp_f32_e32 v45, v45
	v_exp_f32_e32 v46, v46
	v_exp_f32_e32 v47, v47
	v_pk_add_f32 v[50:51], v[50:51], 1.0 op_sel_hi:[1,0]
	v_pk_add_f32 v[52:53], v[52:53], 1.0 op_sel_hi:[1,0]
	v_pk_add_f32 v[44:45], v[44:45], 1.0 op_sel_hi:[1,0]
	v_pk_add_f32 v[46:47], v[46:47], 1.0 op_sel_hi:[1,0]
	v_rcp_f32_e32 v50, v50
	v_rcp_f32_e32 v51, v51
	v_rcp_f32_e32 v52, v52
	v_rcp_f32_e32 v53, v53
	v_rcp_f32_e32 v44, v44
	v_rcp_f32_e32 v45, v45
	v_rcp_f32_e32 v46, v46
	v_rcp_f32_e32 v47, v47
	v_pk_mul_f32 v[34:35], v[38:39], v[34:35]
	v_pk_mul_f32 v[32:33], v[36:37], v[32:33]
	v_lshl_add_u64 v[228:229], v[228:229], 0, s[100:101]
	v_pk_mul_f32 v[40:41], v[50:51], v[40:41]
	v_pk_mul_f32 v[42:43], v[52:53], v[42:43]
	v_pk_mul_f32 v[36:37], v[44:45], v[32:33]
	v_pk_mul_f32 v[38:39], v[46:47], v[34:35]
	v_cvt_pk_bf16_f32 v32, v40, v41
	v_cvt_pk_bf16_f32 v33, v42, v43
	v_cvt_pk_bf16_f32 v34, v36, v37
	v_pk_mul_f32 v[36:37], v[30:31], s[8:9] op_sel_hi:[1,0]
	v_cvt_pk_bf16_f32 v35, v38, v39
	global_store_dwordx4 v[228:229], v[32:35], off
	v_pk_mul_f32 v[26:27], v[30:31], v[26:27]
	v_pk_mul_f32 v[24:25], v[28:29], v[24:25]
	v_pk_mul_f32 v[34:35], v[28:29], s[8:9] op_sel_hi:[1,0]
	v_pk_mul_f32 v[28:29], v[20:21], s[8:9] op_sel_hi:[1,0]
	v_pk_mul_f32 v[30:31], v[22:23], s[8:9] op_sel_hi:[1,0]
	v_exp_f32_e32 v34, v34
	v_exp_f32_e32 v35, v35
	v_exp_f32_e32 v36, v36
	v_exp_f32_e32 v37, v37
	v_exp_f32_e32 v28, v28
	v_exp_f32_e32 v29, v29
	v_exp_f32_e32 v30, v30
	v_exp_f32_e32 v31, v31
	v_pk_add_f32 v[34:35], v[34:35], 1.0 op_sel_hi:[1,0]
	v_pk_add_f32 v[36:37], v[36:37], 1.0 op_sel_hi:[1,0]
	v_pk_add_f32 v[28:29], v[28:29], 1.0 op_sel_hi:[1,0]
	v_pk_add_f32 v[30:31], v[30:31], 1.0 op_sel_hi:[1,0]
	v_rcp_f32_e32 v34, v34
	v_rcp_f32_e32 v35, v35
	v_rcp_f32_e32 v36, v36
	v_rcp_f32_e32 v37, v37
	v_rcp_f32_e32 v28, v28
	v_rcp_f32_e32 v29, v29
	v_rcp_f32_e32 v30, v30
	v_rcp_f32_e32 v31, v31
	v_pk_mul_f32 v[18:19], v[22:23], v[18:19]
	v_pk_mul_f32 v[16:17], v[20:21], v[16:17]
	v_lshl_add_u64 v[228:229], v[228:229], 0, s[100:101]
	v_pk_mul_f32 v[24:25], v[34:35], v[24:25]
	v_pk_mul_f32 v[26:27], v[36:37], v[26:27]
	v_pk_mul_f32 v[20:21], v[28:29], v[16:17]
	v_pk_mul_f32 v[22:23], v[30:31], v[18:19]
	v_cvt_pk_bf16_f32 v16, v24, v25
	v_cvt_pk_bf16_f32 v17, v26, v27
	v_cvt_pk_bf16_f32 v18, v20, v21
	v_pk_mul_f32 v[20:21], v[14:15], s[8:9] op_sel_hi:[1,0]
	v_cvt_pk_bf16_f32 v19, v22, v23
	global_store_dwordx4 v[228:229], v[16:19], off
	v_pk_mul_f32 v[10:11], v[14:15], v[10:11]
	v_pk_mul_f32 v[8:9], v[12:13], v[8:9]
	v_pk_mul_f32 v[18:19], v[12:13], s[8:9] op_sel_hi:[1,0]
	v_pk_mul_f32 v[12:13], v[4:5], s[8:9] op_sel_hi:[1,0]
	v_pk_mul_f32 v[14:15], v[6:7], s[8:9] op_sel_hi:[1,0]
	v_exp_f32_e32 v18, v18
	v_exp_f32_e32 v19, v19
	v_exp_f32_e32 v20, v20
	v_exp_f32_e32 v21, v21
	v_exp_f32_e32 v12, v12
	v_exp_f32_e32 v13, v13
	v_exp_f32_e32 v14, v14
	v_exp_f32_e32 v15, v15
	v_pk_add_f32 v[18:19], v[18:19], 1.0 op_sel_hi:[1,0]
	v_pk_add_f32 v[20:21], v[20:21], 1.0 op_sel_hi:[1,0]
	v_pk_add_f32 v[12:13], v[12:13], 1.0 op_sel_hi:[1,0]
	v_pk_add_f32 v[14:15], v[14:15], 1.0 op_sel_hi:[1,0]
	v_rcp_f32_e32 v18, v18
	v_rcp_f32_e32 v19, v19
	v_rcp_f32_e32 v20, v20
	v_rcp_f32_e32 v21, v21
	v_rcp_f32_e32 v12, v12
	v_rcp_f32_e32 v13, v13
	v_rcp_f32_e32 v14, v14
	v_rcp_f32_e32 v15, v15
	v_lshl_add_u64 v[228:229], v[228:229], 0, s[100:101]
	v_pk_mul_f32 v[2:3], v[6:7], v[2:3]
	v_pk_mul_f32 v[0:1], v[4:5], v[0:1]
	s_andn2_b64 vcc, exec, s[4:5]
	s_mov_b64 s[4:5], -1
	v_pk_mul_f32 v[8:9], v[18:19], v[8:9]
	v_pk_mul_f32 v[10:11], v[20:21], v[10:11]
	v_pk_mul_f32 v[4:5], v[12:13], v[0:1]
	v_pk_mul_f32 v[6:7], v[14:15], v[2:3]
	v_cvt_pk_bf16_f32 v0, v8, v9
	v_cvt_pk_bf16_f32 v1, v10, v11
	v_cvt_pk_bf16_f32 v2, v4, v5
	s_nop 0
	v_cvt_pk_bf16_f32 v3, v6, v7
	global_store_dwordx4 v[228:229], v[0:3], off
	s_cbranch_vccnz .LBB0_265
	s_andn2_b64 vcc, exec, s[0:1]
	s_cbranch_vccnz .LBB0_264
	s_barrier
	s_branch .LBB0_264

; __device__ __forceinline__ unsigned cvt_pk_bf16(float lo, float hi) { unsigned r; asm volatile("v_cvt_pk_bf16_f32 %0, %1, %2" : "=v"(r) : "v"(lo), "v"(hi)); return r; }
; __device__ __forceinline__ f32x2p silu_mul2(f32x2p g, f32x2p u) {
;     const f32x2p t = g * (-1.4426950408889634f); f32x2p e; e.x = __builtin_amdgcn_exp2f(t.x); e.y = __builtin_amdgcn_exp2f(t.y);
;     const f32x2p d = e + 1.0f; f32x2p r; r.x = __builtin_amdgcn_rcpf(d.x); r.y = __builtin_amdgcn_rcpf(d.y);
;     return (g * u) * r;
; }
;     __device__ __forceinline__ void operator()(const f32x4 (&acc)[2][2][4][2], const Unit& u, int wr, int wc, int fr, int fq) const {
;         const int row0 = u.pm * BM + wr * 64 + fr, col0 = u.pn * HALF + wc * 32 + 8 * fq;
; #pragma unroll
;         for (int ai = 0; ai < 2; ++ai)
; #pragma unroll
;             for (int m = 0; m < 4; ++m) { bf16_t* rowp = O + (size_t)(row0 + ai * HALF + m * 16) * ldc + col0;
;                 const f32x4 g0 = acc[ai][0][m][0], g1 = acc[ai][0][m][1], u0 = acc[ai][1][m][0], u1 = acc[ai][1][m][1];
;                 const f32x2p a = silu_mul2((f32x2p){g0[0], g0[1]}, (f32x2p){u0[0], u0[1]}), b = silu_mul2((f32x2p){g0[2], g0[3]}, (f32x2p){u0[2], u0[3]});
;                 const f32x2p c = silu_mul2((f32x2p){g1[0], g1[1]}, (f32x2p){u1[0], u1[1]}), d = silu_mul2((f32x2p){g1[2], g1[3]}, (f32x2p){u1[2], u1[3]});
;                 u32x4 w; w.x = cvt_pk_bf16(a.x, a.y); w.y = cvt_pk_bf16(b.x, b.y); w.z = cvt_pk_bf16(c.x, c.y); w.w = cvt_pk_bf16(d.x, d.y);
;                 *(u32x4*)rowp = w; }
.LBB0_1915:
	v_pk_mul_f32 v[158:159], v[124:125], s[8:9] op_sel_hi:[1,0]
	v_pk_mul_f32 v[160:161], v[126:127], s[8:9] op_sel_hi:[1,0]
	v_pk_mul_f32 v[122:123], v[126:127], v[122:123]
	v_pk_mul_f32 v[120:121], v[124:125], v[120:121]
	v_pk_mul_f32 v[124:125], v[116:117], s[8:9] op_sel_hi:[1,0]
	v_pk_mul_f32 v[126:127], v[118:119], s[8:9] op_sel_hi:[1,0]
	v_exp_f32_e32 v158, v158
	v_exp_f32_e32 v159, v159
	v_exp_f32_e32 v160, v160
	v_exp_f32_e32 v161, v161
	v_exp_f32_e32 v124, v124
	v_exp_f32_e32 v125, v125
	v_exp_f32_e32 v126, v126
	v_exp_f32_e32 v127, v127
	v_pk_add_f32 v[158:159], v[158:159], 1.0 op_sel_hi:[1,0]
	v_pk_add_f32 v[160:161], v[160:161], 1.0 op_sel_hi:[1,0]
	v_pk_add_f32 v[124:125], v[124:125], 1.0 op_sel_hi:[1,0]
	v_pk_add_f32 v[126:127], v[126:127], 1.0 op_sel_hi:[1,0]
	v_readlane_b32 s22, v254, 15
	v_rcp_f32_e32 v158, v158
	v_rcp_f32_e32 v159, v159
	v_rcp_f32_e32 v160, v160
	v_rcp_f32_e32 v161, v161
	v_rcp_f32_e32 v124, v124
	v_rcp_f32_e32 v125, v125
	v_rcp_f32_e32 v126, v126
	v_rcp_f32_e32 v127, v127
	v_lshl_add_u32 v146, s41, 7, v150
	v_readlane_b32 s23, v254, 16
	v_lshl_add_u32 v154, s20, 8, v148
	v_ashrrev_i32_e32 v147, 31, v146
	v_mov_b64_e32 v[144:145], s[22:23]
	s_lshl_b32 s100, s40, 4
	s_mov_b32 s101, 0
	s_mul_i32 s96, s40, 0x50
	s_mov_b32 s97, 0
	v_mad_i64_i32 v[156:157], s[22:23], v154, s40, v[144:145]
	v_lshlrev_b64 v[146:147], 1, v[146:147]
	v_pk_mul_f32 v[114:115], v[118:119], v[114:115]
	v_pk_mul_f32 v[112:113], v[116:117], v[112:113]
	v_lshl_add_u64 v[228:229], v[156:157], 0, v[146:147]
	v_pk_mul_f32 v[120:121], v[158:159], v[120:121]
	v_pk_mul_f32 v[122:123], v[160:161], v[122:123]
	v_pk_mul_f32 v[116:117], v[124:125], v[112:113]
	v_pk_mul_f32 v[118:119], v[126:127], v[114:115]
	v_cvt_pk_bf16_f32 v112, v120, v121
	v_cvt_pk_bf16_f32 v113, v122, v123
	v_cvt_pk_bf16_f32 v114, v116, v117
	v_pk_mul_f32 v[116:117], v[110:111], s[8:9] op_sel_hi:[1,0]
	v_cvt_pk_bf16_f32 v115, v118, v119
	global_store_dwordx4 v[228:229], v[112:115], off
	v_pk_mul_f32 v[106:107], v[110:111], v[106:107]
	v_pk_mul_f32 v[104:105], v[108:109], v[104:105]
	v_pk_mul_f32 v[114:115], v[108:109], s[8:9] op_sel_hi:[1,0]
	v_pk_mul_f32 v[108:109], v[100:101], s[8:9] op_sel_hi:[1,0]
	v_pk_mul_f32 v[110:111], v[102:103], s[8:9] op_sel_hi:[1,0]
	v_exp_f32_e32 v114, v114
	v_exp_f32_e32 v115, v115
	v_exp_f32_e32 v116, v116
	v_exp_f32_e32 v117, v117
	v_exp_f32_e32 v108, v108
	v_exp_f32_e32 v109, v109
	v_exp_f32_e32 v110, v110
	v_exp_f32_e32 v111, v111
	v_pk_add_f32 v[114:115], v[114:115], 1.0 op_sel_hi:[1,0]
	v_pk_add_f32 v[116:117], v[116:117], 1.0 op_sel_hi:[1,0]
	v_pk_add_f32 v[108:109], v[108:109], 1.0 op_sel_hi:[1,0]
	v_pk_add_f32 v[110:111], v[110:111], 1.0 op_sel_hi:[1,0]
	v_rcp_f32_e32 v114, v114
	v_rcp_f32_e32 v115, v115
	v_rcp_f32_e32 v116, v116
	v_rcp_f32_e32 v117, v117
	v_rcp_f32_e32 v108, v108
	v_rcp_f32_e32 v109, v109
	v_rcp_f32_e32 v110, v110
	v_rcp_f32_e32 v111, v111
	v_pk_mul_f32 v[98:99], v[102:103], v[98:99]
	v_pk_mul_f32 v[96:97], v[100:101], v[96:97]
	v_lshl_add_u64 v[228:229], v[228:229], 0, s[100:101]
	v_pk_mul_f32 v[104:105], v[114:115], v[104:105]
	v_pk_mul_f32 v[106:107], v[116:117], v[106:107]
	v_pk_mul_f32 v[100:101], v[108:109], v[96:97]
	v_pk_mul_f32 v[102:103], v[110:111], v[98:99]
	v_cvt_pk_bf16_f32 v96, v104, v105
	v_cvt_pk_bf16_f32 v97, v106, v107
	v_cvt_pk_bf16_f32 v98, v100, v101
	v_pk_mul_f32 v[100:101], v[94:95], s[8:9] op_sel_hi:[1,0]
	v_cvt_pk_bf16_f32 v99, v102, v103
	global_store_dwordx4 v[228:229], v[96:99], off
	v_pk_mul_f32 v[90:91], v[94:95], v[90:91]
	v_pk_mul_f32 v[88:89], v[92:93], v[88:89]
	v_pk_mul_f32 v[98:99], v[92:93], s[8:9] op_sel_hi:[1,0]
	v_pk_mul_f32 v[92:93], v[84:85], s[8:9] op_sel_hi:[1,0]
	v_pk_mul_f32 v[94:95], v[86:87], s[8:9] op_sel_hi:[1,0]
	v_exp_f32_e32 v98, v98
	v_exp_f32_e32 v99, v99
	v_exp_f32_e32 v100, v100
	v_exp_f32_e32 v101, v101
	v_exp_f32_e32 v92, v92
	v_exp_f32_e32 v93, v93
	v_exp_f32_e32 v94, v94
	v_exp_f32_e32 v95, v95
	v_pk_add_f32 v[98:99], v[98:99], 1.0 op_sel_hi:[1,0]
	v_pk_add_f32 v[100:101], v[100:101], 1.0 op_sel_hi:[1,0]
	v_pk_add_f32 v[92:93], v[92:93], 1.0 op_sel_hi:[1,0]
	v_pk_add_f32 v[94:95], v[94:95], 1.0 op_sel_hi:[1,0]
	v_rcp_f32_e32 v98, v98
	v_rcp_f32_e32 v99, v99
	v_rcp_f32_e32 v100, v100
	v_rcp_f32_e32 v101, v101
	v_rcp_f32_e32 v92, v92
	v_rcp_f32_e32 v93, v93
	v_rcp_f32_e32 v94, v94
	v_rcp_f32_e32 v95, v95
	v_pk_mul_f32 v[82:83], v[86:87], v[82:83]
	v_pk_mul_f32 v[80:81], v[84:85], v[80:81]
	v_lshl_add_u64 v[228:229], v[228:229], 0, s[100:101]
	v_pk_mul_f32 v[88:89], v[98:99], v[88:89]
	v_pk_mul_f32 v[90:91], v[100:101], v[90:91]
	v_pk_mul_f32 v[84:85], v[92:93], v[80:81]
	v_pk_mul_f32 v[86:87], v[94:95], v[82:83]
	v_cvt_pk_bf16_f32 v80, v88, v89
	v_cvt_pk_bf16_f32 v81, v90, v91
	v_cvt_pk_bf16_f32 v82, v84, v85
	v_pk_mul_f32 v[84:85], v[78:79], s[8:9] op_sel_hi:[1,0]
	v_cvt_pk_bf16_f32 v83, v86, v87
	global_store_dwordx4 v[228:229], v[80:83], off
	v_pk_mul_f32 v[74:75], v[78:79], v[74:75]
	v_pk_mul_f32 v[72:73], v[76:77], v[72:73]
	v_pk_mul_f32 v[82:83], v[76:77], s[8:9] op_sel_hi:[1,0]
	v_pk_mul_f32 v[76:77], v[68:69], s[8:9] op_sel_hi:[1,0]
	v_pk_mul_f32 v[78:79], v[70:71], s[8:9] op_sel_hi:[1,0]
	v_exp_f32_e32 v82, v82
	v_exp_f32_e32 v83, v83
	v_exp_f32_e32 v84, v84
	v_exp_f32_e32 v85, v85
	v_exp_f32_e32 v76, v76
	v_exp_f32_e32 v77, v77
	v_exp_f32_e32 v78, v78
	v_exp_f32_e32 v79, v79
	v_pk_add_f32 v[82:83], v[82:83], 1.0 op_sel_hi:[1,0]
	v_pk_add_f32 v[84:85], v[84:85], 1.0 op_sel_hi:[1,0]
	v_pk_add_f32 v[76:77], v[76:77], 1.0 op_sel_hi:[1,0]
	v_pk_add_f32 v[78:79], v[78:79], 1.0 op_sel_hi:[1,0]
	v_rcp_f32_e32 v82, v82
	v_rcp_f32_e32 v83, v83
; __device__ __forceinline__ unsigned cvt_pk_bf16(float lo, float hi) { unsigned r; asm volatile("v_cvt_pk_bf16_f32 %0, %1, %2" : "=v"(r) : "v"(lo), "v"(hi)); return r; }
; __device__ __forceinline__ f32x2p silu_mul2(f32x2p g, f32x2p u) {
;     const f32x2p t = g * (-1.4426950408889634f); f32x2p e; e.x = __builtin_amdgcn_exp2f(t.x); e.y = __builtin_amdgcn_exp2f(t.y);
;     const f32x2p d = e + 1.0f; f32x2p r; r.x = __builtin_amdgcn_rcpf(d.x); r.y = __builtin_amdgcn_rcpf(d.y);
;     return (g * u) * r;
; }
;     __device__ __forceinline__ void operator()(const f32x4 (&acc)[2][2][4][2], const Unit& u, int wr, int wc, int fr, int fq) const {
;     ...
;             for (int m = 0; m < 4; ++m) { bf16_t* rowp = O + (size_t)(row0 + ai * HALF + m * 16) * ldc + col0;
;                 const f32x4 g0 = acc[ai][0][m][0], g1 = acc[ai][0][m][1], u0 = acc[ai][1][m][0], u1 = acc[ai][1][m][1];
;                 const f32x2p a = silu_mul2((f32x2p){g0[0], g0[1]}, (f32x2p){u0[0], u0[1]}), b = silu_mul2((f32x2p){g0[2], g0[3]}, (f32x2p){u0[2], u0[3]});
;                 const f32x2p c = silu_mul2((f32x2p){g1[0], g1[1]}, (f32x2p){u1[0], u1[1]}), d = silu_mul2((f32x2p){g1[2], g1[3]}, (f32x2p){u1[2], u1[3]});
;                 u32x4 w; w.x = cvt_pk_bf16(a.x, a.y); w.y = cvt_pk_bf16(b.x, b.y); w.z = cvt_pk_bf16(c.x, c.y); w.w = cvt_pk_bf16(d.x, d.y);
;                 *(u32x4*)rowp = w; }
	v_rcp_f32_e32 v84, v84
	v_rcp_f32_e32 v85, v85
	v_rcp_f32_e32 v76, v76
	v_rcp_f32_e32 v77, v77
	v_rcp_f32_e32 v78, v78
	v_rcp_f32_e32 v79, v79
	v_pk_mul_f32 v[66:67], v[70:71], v[66:67]
	v_pk_mul_f32 v[64:65], v[68:69], v[64:65]
	v_lshl_add_u64 v[228:229], v[228:229], 0, s[100:101]
	v_pk_mul_f32 v[72:73], v[82:83], v[72:73]
	v_pk_mul_f32 v[74:75], v[84:85], v[74:75]
	v_pk_mul_f32 v[68:69], v[76:77], v[64:65]
	v_pk_mul_f32 v[70:71], v[78:79], v[66:67]
	v_cvt_pk_bf16_f32 v64, v72, v73
	v_cvt_pk_bf16_f32 v65, v74, v75
	v_cvt_pk_bf16_f32 v66, v68, v69
	v_pk_mul_f32 v[68:69], v[62:63], s[8:9] op_sel_hi:[1,0]
	v_cvt_pk_bf16_f32 v67, v70, v71
	global_store_dwordx4 v[228:229], v[64:67], off
	v_pk_mul_f32 v[58:59], v[62:63], v[58:59]
	v_pk_mul_f32 v[56:57], v[60:61], v[56:57]
	v_pk_mul_f32 v[66:67], v[60:61], s[8:9] op_sel_hi:[1,0]
	v_pk_mul_f32 v[60:61], v[52:53], s[8:9] op_sel_hi:[1,0]
	v_pk_mul_f32 v[62:63], v[54:55], s[8:9] op_sel_hi:[1,0]
	v_exp_f32_e32 v66, v66
	v_exp_f32_e32 v67, v67
	v_exp_f32_e32 v68, v68
	v_exp_f32_e32 v69, v69
	v_exp_f32_e32 v60, v60
	v_exp_f32_e32 v61, v61
	v_exp_f32_e32 v62, v62
	v_exp_f32_e32 v63, v63
	v_pk_add_f32 v[66:67], v[66:67], 1.0 op_sel_hi:[1,0]
	v_pk_add_f32 v[68:69], v[68:69], 1.0 op_sel_hi:[1,0]
	v_pk_add_f32 v[60:61], v[60:61], 1.0 op_sel_hi:[1,0]
	v_pk_add_f32 v[62:63], v[62:63], 1.0 op_sel_hi:[1,0]
	v_rcp_f32_e32 v66, v66
	v_rcp_f32_e32 v67, v67
	v_rcp_f32_e32 v68, v68
	v_rcp_f32_e32 v69, v69
	v_rcp_f32_e32 v60, v60
	v_rcp_f32_e32 v61, v61
	v_rcp_f32_e32 v62, v62
	v_rcp_f32_e32 v63, v63
	v_pk_mul_f32 v[50:51], v[54:55], v[50:51]
	v_pk_mul_f32 v[48:49], v[52:53], v[48:49]
	v_lshl_add_u64 v[228:229], v[228:229], 0, s[96:97]
	v_pk_mul_f32 v[56:57], v[66:67], v[56:57]
	v_pk_mul_f32 v[58:59], v[68:69], v[58:59]
	v_pk_mul_f32 v[52:53], v[60:61], v[48:49]
	v_pk_mul_f32 v[54:55], v[62:63], v[50:51]
	v_cvt_pk_bf16_f32 v48, v56, v57
	v_cvt_pk_bf16_f32 v49, v58, v59
	v_cvt_pk_bf16_f32 v50, v52, v53
	v_pk_mul_f32 v[52:53], v[46:47], s[8:9] op_sel_hi:[1,0]
	v_cvt_pk_bf16_f32 v51, v54, v55
	global_store_dwordx4 v[228:229], v[48:51], off
	v_pk_mul_f32 v[42:43], v[46:47], v[42:43]
	v_pk_mul_f32 v[40:41], v[44:45], v[40:41]
	v_pk_mul_f32 v[50:51], v[44:45], s[8:9] op_sel_hi:[1,0]
	v_pk_mul_f32 v[44:45], v[36:37], s[8:9] op_sel_hi:[1,0]
	v_pk_mul_f32 v[46:47], v[38:39], s[8:9] op_sel_hi:[1,0]
	v_exp_f32_e32 v50, v50
	v_exp_f32_e32 v51, v51
	v_exp_f32_e32 v52, v52
	v_exp_f32_e32 v53, v53
	v_exp_f32_e32 v44, v44
	v_exp_f32_e32 v45, v45
	v_exp_f32_e32 v46, v46
	v_exp_f32_e32 v47, v47
	v_pk_add_f32 v[50:51], v[50:51], 1.0 op_sel_hi:[1,0]
	v_pk_add_f32 v[52:53], v[52:53], 1.0 op_sel_hi:[1,0]
	v_pk_add_f32 v[44:45], v[44:45], 1.0 op_sel_hi:[1,0]
	v_pk_add_f32 v[46:47], v[46:47], 1.0 op_sel_hi:[1,0]
	v_rcp_f32_e32 v50, v50
	v_rcp_f32_e32 v51, v51
	v_rcp_f32_e32 v52, v52
	v_rcp_f32_e32 v53, v53
	v_rcp_f32_e32 v44, v44
	v_rcp_f32_e32 v45, v45
	v_rcp_f32_e32 v46, v46
	v_rcp_f32_e32 v47, v47
	v_pk_mul_f32 v[34:35], v[38:39], v[34:35]
	v_pk_mul_f32 v[32:33], v[36:37], v[32:33]
	v_lshl_add_u64 v[228:229], v[228:229], 0, s[100:101]
	v_pk_mul_f32 v[40:41], v[50:51], v[40:41]
	v_pk_mul_f32 v[42:43], v[52:53], v[42:43]
	v_pk_mul_f32 v[36:37], v[44:45], v[32:33]
	v_pk_mul_f32 v[38:39], v[46:47], v[34:35]
	v_cvt_pk_bf16_f32 v32, v40, v41
	v_cvt_pk_bf16_f32 v33, v42, v43
	v_cvt_pk_bf16_f32 v34, v36, v37
	v_pk_mul_f32 v[36:37], v[30:31], s[8:9] op_sel_hi:[1,0]
	v_cvt_pk_bf16_f32 v35, v38, v39
	global_store_dwordx4 v[228:229], v[32:35], off
	v_pk_mul_f32 v[26:27], v[30:31], v[26:27]
	v_pk_mul_f32 v[24:25], v[28:29], v[24:25]
	v_pk_mul_f32 v[34:35], v[28:29], s[8:9] op_sel_hi:[1,0]
	v_pk_mul_f32 v[28:29], v[20:21], s[8:9] op_sel_hi:[1,0]
	v_pk_mul_f32 v[30:31], v[22:23], s[8:9] op_sel_hi:[1,0]
	v_exp_f32_e32 v34, v34
	v_exp_f32_e32 v35, v35
	v_exp_f32_e32 v36, v36
	v_exp_f32_e32 v37, v37
	v_exp_f32_e32 v28, v28
	v_exp_f32_e32 v29, v29
	v_exp_f32_e32 v30, v30
	v_exp_f32_e32 v31, v31
	v_pk_add_f32 v[34:35], v[34:35], 1.0 op_sel_hi:[1,0]
	v_pk_add_f32 v[36:37], v[36:37], 1.0 op_sel_hi:[1,0]
	v_pk_add_f32 v[28:29], v[28:29], 1.0 op_sel_hi:[1,0]
	v_pk_add_f32 v[30:31], v[30:31], 1.0 op_sel_hi:[1,0]
	v_rcp_f32_e32 v34, v34
	v_rcp_f32_e32 v35, v35
	v_rcp_f32_e32 v36, v36
	v_rcp_f32_e32 v37, v37
	v_rcp_f32_e32 v28, v28
	v_rcp_f32_e32 v29, v29
	v_rcp_f32_e32 v30, v30
	v_rcp_f32_e32 v31, v31
	v_pk_mul_f32 v[18:19], v[22:23], v[18:19]
	v_pk_mul_f32 v[16:17], v[20:21], v[16:17]
	v_lshl_add_u64 v[228:229], v[228:229], 0, s[100:101]
	v_pk_mul_f32 v[24:25], v[34:35], v[24:25]
	v_pk_mul_f32 v[26:27], v[36:37], v[26:27]
	v_pk_mul_f32 v[20:21], v[28:29], v[16:17]
	v_pk_mul_f32 v[22:23], v[30:31], v[18:19]
	v_cvt_pk_bf16_f32 v16, v24, v25
	v_cvt_pk_bf16_f32 v17, v26, v27
	v_cvt_pk_bf16_f32 v18, v20, v21
	v_pk_mul_f32 v[20:21], v[14:15], s[8:9] op_sel_hi:[1,0]
	v_cvt_pk_bf16_f32 v19, v22, v23
	global_store_dwordx4 v[228:229], v[16:19], off
	v_pk_mul_f32 v[10:11], v[14:15], v[10:11]
	v_pk_mul_f32 v[8:9], v[12:13], v[8:9]
	v_pk_mul_f32 v[18:19], v[12:13], s[8:9] op_sel_hi:[1,0]
	v_pk_mul_f32 v[12:13], v[4:5], s[8:9] op_sel_hi:[1,0]
	v_pk_mul_f32 v[14:15], v[6:7], s[8:9] op_sel_hi:[1,0]
	v_exp_f32_e32 v18, v18
	v_exp_f32_e32 v19, v19
	v_exp_f32_e32 v20, v20
	v_exp_f32_e32 v21, v21
	v_exp_f32_e32 v12, v12
	v_exp_f32_e32 v13, v13
	v_exp_f32_e32 v14, v14
	v_exp_f32_e32 v15, v15
	v_pk_add_f32 v[18:19], v[18:19], 1.0 op_sel_hi:[1,0]
	v_pk_add_f32 v[20:21], v[20:21], 1.0 op_sel_hi:[1,0]
	v_pk_add_f32 v[12:13], v[12:13], 1.0 op_sel_hi:[1,0]
	v_pk_add_f32 v[14:15], v[14:15], 1.0 op_sel_hi:[1,0]
	v_rcp_f32_e32 v18, v18
	v_rcp_f32_e32 v19, v19
	v_rcp_f32_e32 v20, v20
	v_rcp_f32_e32 v21, v21
	v_rcp_f32_e32 v12, v12
	v_rcp_f32_e32 v13, v13
	v_rcp_f32_e32 v14, v14
	v_rcp_f32_e32 v15, v15
	v_lshl_add_u64 v[228:229], v[228:229], 0, s[100:101]
	v_pk_mul_f32 v[2:3], v[6:7], v[2:3]
	v_pk_mul_f32 v[0:1], v[4:5], v[0:1]
	s_andn2_b64 vcc, exec, s[4:5]
	s_mov_b64 s[4:5], -1
	v_pk_mul_f32 v[8:9], v[18:19], v[8:9]
	v_pk_mul_f32 v[10:11], v[20:21], v[10:11]
	v_pk_mul_f32 v[4:5], v[12:13], v[0:1]
	v_pk_mul_f32 v[6:7], v[14:15], v[2:3]
	v_cvt_pk_bf16_f32 v0, v8, v9
	v_cvt_pk_bf16_f32 v1, v10, v11
	v_cvt_pk_bf16_f32 v2, v4, v5
	s_nop 0
	v_cvt_pk_bf16_f32 v3, v6, v7
	global_store_dwordx4 v[228:229], v[0:3], off
	s_cbranch_vccnz .LBB0_1908
	s_andn2_b64 vcc, exec, s[0:1]
	s_cbranch_vccnz .LBB0_1907
	s_barrier
	s_branch .LBB0_1907
